# grid barrier: cache invalidate issued with the arrival atomic (CU is quiescent there) instead of after the release is observed
# speedup vs baseline: 1.0276x; 1.0069x over previous
.LBB0_583:
	s_lshl_b32 s24, s36, 6
	s_add_i32 s6, s24, 0x500
	s_mov_b32 s7, 0
	s_lshl_b64 s[4:5], s[6:7], 2
	s_add_u32 s4, s2, s4
	s_addc_u32 s5, s3, s5
	v_mov_b32_e32 v1, 1
	v_mov_b64_e32 v[4:5], s[4:5]
	flat_atomic_add v1, v[4:5], v1 sc0
	buffer_inv sc1
	v_cvt_f32_u32_e32 v3, v2
	v_sub_u32_e32 v4, 0, v2
	v_rcp_iflag_f32_e32 v3, v3
	s_nop 0
	v_mul_f32_e32 v3, 0x4f7ffffe, v3
	v_cvt_u32_f32_e32 v3, v3
	v_mul_lo_u32 v4, v4, v3
	v_mul_hi_u32 v4, v3, v4
	v_add_u32_e32 v3, v3, v4
	s_waitcnt vmcnt(0) lgkmcnt(0)
	v_mul_hi_u32 v3, v1, v3
	v_mul_lo_u32 v5, v3, v2
	v_add_u32_e32 v4, 1, v1
	v_sub_u32_e32 v1, v1, v5
	v_add_u32_e32 v6, 1, v3
	v_cmp_ge_u32_e32 vcc, v1, v2
	v_sub_u32_e32 v5, v1, v2
	s_nop 0
	v_cndmask_b32_e32 v3, v3, v6, vcc
	v_cndmask_b32_e32 v1, v1, v5, vcc
	v_add_u32_e32 v5, 1, v3
	v_cmp_ge_u32_e32 vcc, v1, v2
	s_nop 1
	v_cndmask_b32_e32 v1, v3, v5, vcc
	v_mad_u64_u32 v[2:3], s[4:5], v2, v1, v[2:3]
	v_cmp_ne_u32_e32 vcc, v4, v2
	s_and_saveexec_b64 s[4:5], vcc
	s_xor_b64 s[4:5], exec, s[4:5]
	s_cbranch_execz .LBB0_596
	s_add_i32 s6, s24, 0x900
	s_lshl_b64 s[6:7], s[6:7], 2
	s_add_u32 s8, s2, s6
	s_addc_u32 s9, s3, s7
	v_mov_b64_e32 v[2:3], s[8:9]
	flat_load_dword v0, v[2:3] sc1
	s_waitcnt vmcnt(0) lgkmcnt(0)
	v_cmp_eq_u32_e32 vcc, v0, v1
	s_and_saveexec_b64 s[6:7], vcc
	s_cbranch_execz .LBB0_595
	s_mov_b32 s25, 1
	s_mov_b64 s[10:11], 0
	s_branch .LBB0_587

.LBB0_595:
	s_or_b64 exec, exec, s[6:7]
	s_waitcnt vmcnt(0) lgkmcnt(0)
	s_waitcnt vmcnt(0)

.LBB0_611:
	s_or_b64 exec, exec, s[4:5]
	s_add_i32 s4, s24, 0x900
	s_mov_b32 s5, 0
	s_lshl_b64 s[4:5], s[4:5], 2
	s_add_u32 s2, s2, s4
	s_addc_u32 s3, s3, s5
	v_mov_b32_e32 v2, 1
	v_mov_b64_e32 v[0:1], s[2:3]
	s_waitcnt vmcnt(0) lgkmcnt(0)
	flat_atomic_add v[0:1], v2
	s_waitcnt vmcnt(0)

.LBB0_613:
	s_or_b64 exec, exec, s[4:5]
	s_add_i32 s90, s24, 0x900
	s_lshl_b64 s[4:5], s[90:91], 2
	s_add_u32 s4, s36, s4
	s_addc_u32 s5, s37, s5
	v_mov_b64_e32 v[0:1], s[4:5]
	s_waitcnt vmcnt(0) lgkmcnt(0)
	flat_atomic_add v[0:1], v217
	s_waitcnt vmcnt(0)

.LBB0_635:
	s_lshl_b32 s24, s33, 6
	s_add_i32 s90, s24, 0x500
	s_lshl_b64 s[4:5], s[90:91], 2
	s_add_u32 s4, s36, s4
	s_addc_u32 s5, s37, s5
	v_mov_b64_e32 v[4:5], s[4:5]
	flat_atomic_add v1, v[4:5], v217 sc0
	buffer_inv sc1
	v_cvt_f32_u32_e32 v3, v2
	v_sub_u32_e32 v4, 0, v2
	v_rcp_iflag_f32_e32 v3, v3
	s_nop 0
	v_mul_f32_e32 v3, 0x4f7ffffe, v3
	v_cvt_u32_f32_e32 v3, v3
	v_mul_lo_u32 v4, v4, v3
	v_mul_hi_u32 v4, v3, v4
	v_add_u32_e32 v3, v3, v4
	s_waitcnt vmcnt(0) lgkmcnt(0)
	v_mul_hi_u32 v3, v1, v3
	v_mul_lo_u32 v5, v3, v2
	v_add_u32_e32 v4, 1, v1
	v_sub_u32_e32 v1, v1, v5
	v_add_u32_e32 v6, 1, v3
	v_cmp_ge_u32_e32 vcc, v1, v2
	v_sub_u32_e32 v5, v1, v2
	s_nop 0
	v_cndmask_b32_e32 v3, v3, v6, vcc
	v_cndmask_b32_e32 v1, v1, v5, vcc
	v_add_u32_e32 v5, 1, v3
	v_cmp_ge_u32_e32 vcc, v1, v2
	s_nop 1
	v_cndmask_b32_e32 v1, v3, v5, vcc
	v_mad_u64_u32 v[2:3], s[4:5], v2, v1, v[2:3]
	v_cmp_ne_u32_e32 vcc, v4, v2
	s_and_saveexec_b64 s[4:5], vcc
	s_xor_b64 s[4:5], exec, s[4:5]
	s_cbranch_execz .LBB0_648
	s_add_i32 s90, s24, 0x900
	s_lshl_b64 s[6:7], s[90:91], 2
	s_add_u32 s8, s36, s6
	s_addc_u32 s9, s37, s7
	v_mov_b64_e32 v[2:3], s[8:9]
	flat_load_dword v0, v[2:3] sc1
	s_waitcnt vmcnt(0) lgkmcnt(0)
	v_cmp_eq_u32_e32 vcc, v0, v1
	s_and_saveexec_b64 s[6:7], vcc
	s_cbranch_execz .LBB0_647
	s_mov_b32 s25, 1
	s_mov_b64 s[10:11], 0
	s_branch .LBB0_639

.LBB0_960:
	s_lshl_b32 s24, s33, 6
	s_add_i32 s90, s24, 0x500
	s_lshl_b64 s[4:5], s[90:91], 2
	s_add_u32 s4, s50, s4
	s_addc_u32 s5, s51, s5
	v_mov_b64_e32 v[4:5], s[4:5]
	flat_atomic_add v3, v[4:5], v217 sc0
	buffer_inv sc1
	v_cvt_f32_u32_e32 v1, v2
	v_sub_u32_e32 v4, 0, v2
	v_rcp_iflag_f32_e32 v1, v1
	s_nop 0
	v_mul_f32_e32 v1, 0x4f7ffffe, v1
	v_cvt_u32_f32_e32 v1, v1
	v_mul_lo_u32 v4, v4, v1
	v_mul_hi_u32 v4, v1, v4
	v_add_u32_e32 v1, v1, v4
	s_waitcnt vmcnt(0) lgkmcnt(0)
	v_mul_hi_u32 v1, v3, v1
	v_mul_lo_u32 v4, v1, v2
	v_sub_u32_e32 v4, v3, v4
	v_cmp_ge_u32_e32 vcc, v4, v2
	v_add_u32_e32 v5, 1, v1
	s_nop 0
	v_cndmask_b32_e32 v1, v1, v5, vcc
	v_sub_u32_e32 v5, v4, v2
	v_cndmask_b32_e32 v4, v4, v5, vcc
	v_cmp_ge_u32_e32 vcc, v4, v2
	v_add_u32_e32 v4, 1, v1
	s_nop 0
	v_cndmask_b32_e32 v1, v1, v4, vcc
	v_add_u32_e32 v4, 1, v3
	v_mad_u64_u32 v[2:3], s[4:5], v2, v1, v[2:3]
	v_cmp_ne_u32_e32 vcc, v4, v2
	s_and_saveexec_b64 s[4:5], vcc
	s_xor_b64 s[4:5], exec, s[4:5]
	s_cbranch_execz .LBB0_973
	s_add_i32 s90, s24, 0x900
	s_lshl_b64 s[6:7], s[90:91], 2
	s_add_u32 s8, s50, s6
	s_addc_u32 s9, s51, s7
	v_mov_b64_e32 v[2:3], s[8:9]
	flat_load_dword v0, v[2:3] sc1
	s_waitcnt vmcnt(0) lgkmcnt(0)
	v_cmp_eq_u32_e32 vcc, v0, v1
	s_and_saveexec_b64 s[6:7], vcc
	s_cbranch_execz .LBB0_972
	s_mov_b32 s25, 1
	s_mov_b64 s[10:11], 0
	s_branch .LBB0_964

.LBB0_988:
	s_or_b64 exec, exec, s[4:5]
	s_add_i32 s90, s24, 0x900
	s_lshl_b64 s[4:5], s[90:91], 2
	s_add_u32 s4, s50, s4
	s_addc_u32 s5, s51, s5
	v_mov_b64_e32 v[0:1], s[4:5]
	s_waitcnt vmcnt(0) lgkmcnt(0)
	flat_atomic_add v[0:1], v217
	s_waitcnt vmcnt(0)

.LBB0_1289:
	s_lshl_b32 s24, s33, 6
	s_add_i32 s4, s24, 0x500
	s_mov_b32 s5, s91
	s_lshl_b64 s[4:5], s[4:5], 2
	s_add_u32 s4, s56, s4
	s_addc_u32 s5, s57, s5
	v_mov_b64_e32 v[4:5], s[4:5]
	flat_atomic_add v3, v[4:5], v217 sc0
	buffer_inv sc1
	v_cvt_f32_u32_e32 v1, v2
	v_sub_u32_e32 v4, 0, v2
	v_rcp_iflag_f32_e32 v1, v1
	s_nop 0
	v_mul_f32_e32 v1, 0x4f7ffffe, v1
	v_cvt_u32_f32_e32 v1, v1
	v_mul_lo_u32 v4, v4, v1
	v_mul_hi_u32 v4, v1, v4
	v_add_u32_e32 v1, v1, v4
	s_waitcnt vmcnt(0) lgkmcnt(0)
	v_mul_hi_u32 v1, v3, v1
	v_mul_lo_u32 v4, v1, v2
	v_sub_u32_e32 v4, v3, v4
	v_cmp_ge_u32_e32 vcc, v4, v2
	v_add_u32_e32 v5, 1, v1
	s_nop 0
	v_cndmask_b32_e32 v1, v1, v5, vcc
	v_sub_u32_e32 v5, v4, v2
	v_cndmask_b32_e32 v4, v4, v5, vcc
	v_cmp_ge_u32_e32 vcc, v4, v2
	v_add_u32_e32 v4, 1, v1
	s_nop 0
	v_cndmask_b32_e32 v1, v1, v4, vcc
	v_add_u32_e32 v4, 1, v3
	v_mad_u64_u32 v[2:3], s[4:5], v2, v1, v[2:3]
	v_cmp_ne_u32_e32 vcc, v4, v2
	s_and_saveexec_b64 s[4:5], vcc
	s_xor_b64 s[4:5], exec, s[4:5]
	s_cbranch_execz .LBB0_1302
	s_add_i32 s6, s24, 0x900
	s_mov_b32 s7, s91
	s_lshl_b64 s[6:7], s[6:7], 2
	s_add_u32 s8, s56, s6
	s_addc_u32 s9, s57, s7
	v_mov_b64_e32 v[2:3], s[8:9]
	flat_load_dword v0, v[2:3] sc1
	s_waitcnt vmcnt(0) lgkmcnt(0)
	v_cmp_eq_u32_e32 vcc, v0, v1
	s_and_saveexec_b64 s[6:7], vcc
	s_cbranch_execz .LBB0_1301
	s_mov_b32 s25, 1
	s_mov_b64 s[10:11], 0
	s_branch .LBB0_1293

.LBB0_1317:
	s_or_b64 exec, exec, s[4:5]
	s_add_i32 s4, s24, 0x900
	s_mov_b32 s5, s91
	s_lshl_b64 s[4:5], s[4:5], 2
	s_add_u32 s4, s56, s4
	s_addc_u32 s5, s57, s5
	v_mov_b64_e32 v[0:1], s[4:5]
	s_waitcnt vmcnt(0) lgkmcnt(0)
	flat_atomic_add v[0:1], v217
	s_waitcnt vmcnt(0)

.LBB0_1717:
	s_lshl_b32 s8, s8, 6
	s_add_i32 s4, s8, 0x500
	s_mov_b32 s5, s91
	s_lshl_b64 s[4:5], s[4:5], 2
	s_add_u32 s4, s46, s4
	s_addc_u32 s5, s47, s5
	v_mov_b64_e32 v[4:5], s[4:5]
	flat_atomic_add v3, v[4:5], v217 sc0
	buffer_inv sc1
	v_cvt_f32_u32_e32 v1, v2
	v_sub_u32_e32 v4, 0, v2
	v_rcp_iflag_f32_e32 v1, v1
	s_nop 0
	v_mul_f32_e32 v1, 0x4f7ffffe, v1
	v_cvt_u32_f32_e32 v1, v1
	v_mul_lo_u32 v4, v4, v1
	v_mul_hi_u32 v4, v1, v4
	v_add_u32_e32 v1, v1, v4
	s_waitcnt vmcnt(0) lgkmcnt(0)
	v_mul_hi_u32 v1, v3, v1
	v_mul_lo_u32 v4, v1, v2
	v_sub_u32_e32 v4, v3, v4
	v_cmp_ge_u32_e32 vcc, v4, v2
	v_add_u32_e32 v5, 1, v1
	s_nop 0
	v_cndmask_b32_e32 v1, v1, v5, vcc
	v_sub_u32_e32 v5, v4, v2
	v_cndmask_b32_e32 v4, v4, v5, vcc
	v_cmp_ge_u32_e32 vcc, v4, v2
	v_add_u32_e32 v4, 1, v1
	s_nop 0
	v_cndmask_b32_e32 v1, v1, v4, vcc
	v_add_u32_e32 v4, 1, v3
	v_mad_u64_u32 v[2:3], s[4:5], v2, v1, v[2:3]
	v_cmp_ne_u32_e32 vcc, v4, v2
	s_and_saveexec_b64 s[4:5], vcc
	s_xor_b64 s[4:5], exec, s[4:5]
	s_cbranch_execz .LBB0_1730
	s_add_i32 s6, s8, 0x900
	s_mov_b32 s7, s91
	s_lshl_b64 s[6:7], s[6:7], 2
	s_add_u32 s10, s46, s6
	s_addc_u32 s11, s47, s7
	v_mov_b64_e32 v[2:3], s[10:11]
	flat_load_dword v0, v[2:3] sc1
	s_waitcnt vmcnt(0) lgkmcnt(0)
	v_cmp_eq_u32_e32 vcc, v0, v1
	s_and_saveexec_b64 s[6:7], vcc
	s_cbranch_execz .LBB0_1729
	s_mov_b32 s9, 1
	s_mov_b64 s[12:13], 0
	s_branch .LBB0_1721

.LBB0_1745:
	s_or_b64 exec, exec, s[4:5]
	s_add_i32 s4, s8, 0x900
	s_mov_b32 s5, s91
	s_lshl_b64 s[4:5], s[4:5], 2
	s_add_u32 s4, s46, s4
	s_addc_u32 s5, s47, s5
	v_mov_b64_e32 v[0:1], s[4:5]
	s_waitcnt vmcnt(0) lgkmcnt(0)
	flat_atomic_add v[0:1], v217
	s_waitcnt vmcnt(0)

.LBB0_1828:
	s_lshl_b32 s24, s33, 6
	s_add_i32 s90, s24, 0x500
	s_lshl_b64 s[4:5], s[90:91], 2
	s_add_u32 s4, s36, s4
	s_addc_u32 s5, s37, s5
	v_mov_b64_e32 v[4:5], s[4:5]
	flat_atomic_add v3, v[4:5], v217 sc0
	buffer_inv sc1
	v_cvt_f32_u32_e32 v1, v2
	v_sub_u32_e32 v4, 0, v2
	v_rcp_iflag_f32_e32 v1, v1
	s_nop 0
	v_mul_f32_e32 v1, 0x4f7ffffe, v1
	v_cvt_u32_f32_e32 v1, v1
	v_mul_lo_u32 v4, v4, v1
	v_mul_hi_u32 v4, v1, v4
	v_add_u32_e32 v1, v1, v4
	s_waitcnt vmcnt(0) lgkmcnt(0)
	v_mul_hi_u32 v1, v3, v1
	v_mul_lo_u32 v4, v1, v2
	v_sub_u32_e32 v4, v3, v4
	v_cmp_ge_u32_e32 vcc, v4, v2
	v_add_u32_e32 v5, 1, v1
	s_nop 0
	v_cndmask_b32_e32 v1, v1, v5, vcc
	v_sub_u32_e32 v5, v4, v2
	v_cndmask_b32_e32 v4, v4, v5, vcc
	v_cmp_ge_u32_e32 vcc, v4, v2
	v_add_u32_e32 v4, 1, v1
	s_nop 0
	v_cndmask_b32_e32 v1, v1, v4, vcc
	v_add_u32_e32 v4, 1, v3
	v_mad_u64_u32 v[2:3], s[4:5], v2, v1, v[2:3]
	v_cmp_ne_u32_e32 vcc, v4, v2
	s_and_saveexec_b64 s[4:5], vcc
	s_xor_b64 s[4:5], exec, s[4:5]
	s_cbranch_execz .LBB0_1841
	s_add_i32 s90, s24, 0x900
	s_lshl_b64 s[6:7], s[90:91], 2
	s_add_u32 s8, s36, s6
	s_addc_u32 s9, s37, s7
	v_mov_b64_e32 v[2:3], s[8:9]
	flat_load_dword v0, v[2:3] sc1
	s_waitcnt vmcnt(0) lgkmcnt(0)
	v_cmp_eq_u32_e32 vcc, v0, v1
	s_and_saveexec_b64 s[6:7], vcc
	s_cbranch_execz .LBB0_1840
	s_mov_b32 s25, 1
	s_mov_b64 s[10:11], 0
	s_branch .LBB0_1832
